# k47: k46 + the same gain-vector hoist in the P7 row loop (rotated loop handled through a linearised view)
# baseline (speedup 1.0000x reference)
.LBB0_1156:
	s_or_b64 exec, exec, s[0:1]
	s_waitcnt lgkmcnt(0)
	v_mov_b32_e32 v0, v226
	s_barrier
	s_nop 0
	v_readfirstlane_b32 s0, v0
	s_ashr_i32 s0, s0, 6
	s_add_i32 s8, s85, s0
	s_cmp_lt_i32 s8, s73
	s_cbranch_scc1 .LBB0_1167
	v_and_b32_e32 v2, 63, v0
	v_readlane_b32 s12, v254, 0
	s_ashr_i32 s9, s8, 31
	v_lshlrev_b32_e32 v0, 5, v2
	v_mov_b32_e32 v1, 0
	v_readlane_b32 s14, v254, 2
	v_readlane_b32 s15, v254, 3
	v_readlane_b32 s16, v254, 4
	v_readlane_b32 s17, v254, 5
	s_lshl_b64 s[0:1], s[8:9], 11
	v_readlane_b32 s13, v254, 1
	v_readlane_b32 s18, v254, 6
	v_readlane_b32 s19, v254, 7
	v_lshl_add_u64 v[56:57], s[16:17], 0, v[0:1]
	v_lshl_or_b32 v58, v2, 4, s0
	v_mov_b32_e32 v59, s1
	s_lshl_b64 s[0:1], s[8:9], 10
	s_mov_b32 s14, 0xffe00000
	s_mov_b32 s16, 0xfff00000
	v_cmp_eq_u32_e64 s[6:7], 0, v2
	s_lshl_b64 s[10:11], s[8:9], 2
	v_lshl_or_b32 v60, v2, 3, s0
	v_mov_b32_e32 v61, s1
	s_mov_b32 s12, 0x3b808081
	v_mov_b32_e32 v84, 0x358637bd
	s_mov_b32 s9, 0xf800000
	v_mov_b32_e32 v85, 0x260
	v_mov_b32_e32 v86, 0x1e00000
	s_mov_b32 s13, 0x37f00000
	s_mov_b32 s18, 0x37f80000
	s_brev_b32 s19, 28
	s_mov_b32 s20, 0x38080000
	s_mov_b32 s15, -1
	s_mov_b32 s17, -1
	global_load_dwordx4 v[132:135], v[56:57], off offset:16
	global_load_dwordx4 v[136:139], v[56:57], off
	global_load_dwordx4 v[140:143], v[56:57], off offset:2064
	global_load_dwordx4 v[144:147], v[56:57], off offset:2048
	s_waitcnt vmcnt(0)
	s_branch .LBB0_1159

.LBB0_1159:
	v_lshl_add_u64 v[62:63], s[92:93], 0, v[58:59]
	v_add_co_u32_e32 v0, vcc, 0x7900000, v62
	v_lshl_add_u64 v[4:5], s[92:93], 0, v[60:61]
	s_nop 0
	v_addc_co_u32_e32 v1, vcc, 0, v63, vcc
	v_add_co_u32_e32 v2, vcc, 0x17b00000, v4
	global_load_dwordx4 v[80:83], v[0:1], off nt
	s_nop 0
	v_addc_co_u32_e32 v3, vcc, 0, v5, vcc
	global_load_dwordx2 v[92:93], v[2:3], off nt
	v_add_co_u32_e32 v6, vcc, 0x2fe00000, v62
	s_waitcnt vmcnt(1)
	v_lshlrev_b32_e32 v78, 16, v80
	v_addc_co_u32_e32 v7, vcc, 0, v63, vcc
	global_load_dwordx4 v[88:91], v[6:7], off nt
	global_load_dwordx4 v[48:51], v[0:1], off offset:1024 nt
	global_load_dwordx2 v[76:77], v[2:3], off offset:512 nt
	global_load_dwordx4 v[52:55], v[6:7], off offset:1024 nt
	v_add_co_u32_e32 v0, vcc, 0x7980000, v62
	s_waitcnt vmcnt(4)
	v_cvt_f32_ubyte1_e32 v95, v92
	v_addc_co_u32_e32 v1, vcc, 0, v63, vcc
	global_load_dwordx4 v[44:47], v[0:1], off nt
	global_load_dwordx4 v[32:35], v[0:1], off offset:1024 nt
	v_add_co_u32_e32 v0, vcc, 0x17b40000, v4
	v_cvt_f32_ubyte0_e32 v94, v92
	s_nop 0
	v_addc_co_u32_e32 v1, vcc, 0, v5, vcc
	global_load_dwordx2 v[74:75], v[0:1], off nt
	global_load_dwordx2 v[72:73], v[0:1], off offset:512 nt
	v_add_co_u32_e32 v0, vcc, 0x2fe80000, v62
	v_cvt_f32_ubyte3_e32 v97, v92
	s_nop 0
	v_addc_co_u32_e32 v1, vcc, 0, v63, vcc
	global_load_dwordx4 v[40:43], v[0:1], off nt
	global_load_dwordx4 v[36:39], v[0:1], off offset:1024 nt
	v_add_co_u32_e32 v0, vcc, 0x7a00000, v62
	v_cvt_f32_ubyte2_e32 v96, v92
	s_nop 0
	v_addc_co_u32_e32 v1, vcc, 0, v63, vcc
	global_load_dwordx4 v[28:31], v[0:1], off nt
	global_load_dwordx4 v[16:19], v[0:1], off offset:1024 nt
	v_add_co_u32_e32 v0, vcc, 0x17b80000, v4
	v_pk_mul_f32 v[96:97], v[96:97], s[12:13] op_sel_hi:[1,0]
	s_nop 0
	v_addc_co_u32_e32 v1, vcc, 0, v5, vcc
	global_load_dwordx2 v[70:71], v[0:1], off nt
	global_load_dwordx2 v[68:69], v[0:1], off offset:512 nt
	v_add_co_u32_e32 v0, vcc, 0x2ff00000, v62
	v_pk_mul_f32 v[94:95], v[94:95], s[12:13] op_sel_hi:[1,0]
	s_nop 0
	v_addc_co_u32_e32 v1, vcc, 0, v63, vcc
	global_load_dwordx4 v[24:27], v[0:1], off nt
	global_load_dwordx4 v[20:23], v[0:1], off offset:1024 nt
	v_add_co_u32_e32 v0, vcc, 0x7a80000, v62
	v_and_b32_e32 v79, 0xffff0000, v80
	s_nop 0
	v_addc_co_u32_e32 v1, vcc, 0, v63, vcc
	v_add_co_u32_e32 v4, vcc, 0x17bc0000, v4
	global_load_dwordx4 v[12:15], v[0:1], off nt
	s_nop 0
	global_load_dwordx4 v[0:3], v[0:1], off offset:1024 nt
	v_addc_co_u32_e32 v5, vcc, 0, v5, vcc
	global_load_dwordx2 v[66:67], v[4:5], off nt
	global_load_dwordx2 v[64:65], v[4:5], off offset:512 nt
	v_add_co_u32_e32 v4, vcc, 0x2ff80000, v62
	v_lshlrev_b32_e32 v80, 16, v81
	s_nop 0
	v_addc_co_u32_e32 v5, vcc, 0, v63, vcc
	global_load_dwordx4 v[8:11], v[4:5], off nt
	s_nop 0
	global_load_dwordx4 v[4:7], v[4:5], off offset:1024 nt
	v_and_b32_e32 v81, 0xffff0000, v81
	v_lshlrev_b32_e32 v110, 16, v82
	v_and_b32_e32 v111, 0xffff0000, v82
	v_lshlrev_b32_e32 v82, 16, v83
	v_and_b32_e32 v83, 0xffff0000, v83
	s_waitcnt vmcnt(21)
	v_lshlrev_b32_e32 v98, 16, v88
	v_and_b32_e32 v99, 0xffff0000, v88
	v_lshlrev_b32_e32 v88, 16, v89
	v_and_b32_e32 v89, 0xffff0000, v89
	v_pk_mul_f32 v[104:105], v[94:95], v[98:99]
	v_pk_mul_f32 v[106:107], v[96:97], v[88:89]
	v_pk_mul_f32 v[94:95], v[104:105], v[104:105]
	v_pk_mul_f32 v[88:89], v[106:107], v[106:107]
	v_lshlrev_b32_e32 v102, 16, v90
	v_pk_mov_b32 v[96:97], v[94:95], v[88:89] op_sel:[1,0]
	v_mov_b32_e32 v95, v89
	v_pk_add_f32 v[108:109], v[96:97], v[94:95]
	v_cvt_f32_ubyte3_e32 v95, v93
	v_cvt_f32_ubyte2_e32 v94, v93
	v_cvt_f32_ubyte1_e32 v89, v93
	v_cvt_f32_ubyte0_e32 v88, v93
	v_pk_mul_f32 v[100:101], v[94:95], s[12:13] op_sel_hi:[1,0]
	v_pk_mul_f32 v[88:89], v[88:89], s[12:13] op_sel_hi:[1,0]
	v_and_b32_e32 v103, 0xffff0000, v90
	v_lshlrev_b32_e32 v90, 16, v91
	v_and_b32_e32 v91, 0xffff0000, v91
	v_pk_mul_f32 v[112:113], v[88:89], v[102:103]
	v_pk_mul_f32 v[114:115], v[100:101], v[90:91]
	v_pk_mul_f32 v[90:91], v[112:113], v[112:113]
	v_pk_mul_f32 v[88:89], v[114:115], v[114:115]
	s_waitcnt vmcnt(20)
	v_lshlrev_b32_e32 v118, 16, v48
	v_pk_mov_b32 v[100:101], v[90:91], v[88:89] op_sel:[1,0]
	v_mov_b32_e32 v91, v89
	v_pk_add_f32 v[116:117], v[100:101], v[90:91]
	v_and_b32_e32 v119, 0xffff0000, v48
	v_lshlrev_b32_e32 v120, 16, v49
	v_and_b32_e32 v121, 0xffff0000, v49
	s_waitcnt vmcnt(19)
	v_cvt_f32_ubyte3_e32 v49, v76
	v_cvt_f32_ubyte2_e32 v48, v76
	v_pk_mul_f32 v[48:49], v[48:49], s[12:13] op_sel_hi:[1,0]
	s_waitcnt vmcnt(18)
	v_lshlrev_b32_e32 v124, 16, v52
	v_and_b32_e32 v125, 0xffff0000, v52
	v_lshlrev_b32_e32 v52, 16, v53
	v_and_b32_e32 v53, 0xffff0000, v53
	v_pk_mul_f32 v[126:127], v[48:49], v[52:53]
	v_cvt_f32_ubyte1_e32 v53, v77
	v_cvt_f32_ubyte0_e32 v52, v77
	v_cvt_f32_ubyte1_e32 v123, v76
	v_cvt_f32_ubyte0_e32 v122, v76
	v_cvt_f32_ubyte3_e32 v49, v77
	v_cvt_f32_ubyte2_e32 v48, v77
	v_pk_mul_f32 v[52:53], v[52:53], s[12:13] op_sel_hi:[1,0]
	v_lshlrev_b32_e32 v76, 16, v54
	v_and_b32_e32 v77, 0xffff0000, v54
	v_pk_mul_f32 v[48:49], v[48:49], s[12:13] op_sel_hi:[1,0]
	v_lshlrev_b32_e32 v54, 16, v55
	v_and_b32_e32 v55, 0xffff0000, v55
	v_pk_mul_f32 v[130:131], v[52:53], v[76:77]
	v_pk_mul_f32 v[128:129], v[48:49], v[54:55]
	v_mul_f32_e32 v52, v130, v130
	v_pk_add_f32 v[48:49], v[108:109], v[108:109] op_sel:[0,1] op_sel_hi:[1,0]
	v_pk_mul_f32 v[122:123], v[122:123], s[12:13] op_sel_hi:[1,0]
	v_mul_f32_e32 v54, v131, v131
	v_mov_b32_e32 v49, v52
	v_pk_add_f32 v[52:53], v[116:117], v[116:117] op_sel:[0,1] op_sel_hi:[1,0]
	v_pk_mul_f32 v[122:123], v[122:123], v[124:125]
	v_mov_b32_e32 v53, v54
	v_pk_add_f32 v[48:49], v[48:49], v[52:53]
	v_mul_f32_e32 v52, v123, v123
	v_mul_f32_e32 v55, v128, v128
	v_pk_fma_f32 v[52:53], v[122:123], v[122:123], v[52:53] op_sel_hi:[1,1,0]
	v_mul_f32_e32 v54, v127, v127
	v_mul_f32_e32 v76, v129, v129
	v_mov_b32_e32 v53, v55
	v_pk_fma_f32 v[54:55], v[126:127], v[126:127], v[54:55] op_sel_hi:[1,1,0]
	v_lshlrev_b32_e32 v124, 16, v50
	v_mov_b32_e32 v55, v76
	v_pk_add_f32 v[52:53], v[52:53], v[54:55]
	v_and_b32_e32 v125, 0xffff0000, v50
	v_pk_add_f32 v[48:49], v[48:49], v[52:53]
	v_lshlrev_b32_e32 v116, 16, v51
	v_add_f32_e32 v48, v48, v49
	v_and_b32_e32 v117, 0xffff0000, v51
	s_nop 0
	v_add_f32_dpp v48, v48, v48 quad_perm:[1,0,3,2] row_mask:0xf bank_mask:0xf bound_ctrl:1
	s_nop 1
	v_add_f32_dpp v48, v48, v48 quad_perm:[2,3,0,1] row_mask:0xf bank_mask:0xf bound_ctrl:1
	s_nop 1
	v_add_f32_dpp v48, v48, v48 row_half_mirror row_mask:0xf bank_mask:0xf bound_ctrl:1
	s_nop 1
	v_add_f32_dpp v48, v48, v48 row_mirror row_mask:0xf bank_mask:0xf bound_ctrl:1
	s_nop 0
	v_readlane_b32 s4, v48, 16
	v_readlane_b32 s5, v48, 48
	v_readlane_b32 s0, v48, 0
	v_readlane_b32 s1, v48, 32
	v_mov_b32_e32 v48, s4
	v_mov_b32_e32 v49, s5
	v_pk_add_f32 v[48:49], s[0:1], v[48:49]
	s_nop 0
	v_add_f32_e32 v48, v48, v49
	v_fmamk_f32 v48, v48, 0x3a800000, v84
	v_rsq_f32_e32 v108, v48
	s_nop 0
	v_pk_mul_f32 v[50:51], v[108:109], v[104:105] op_sel_hi:[0,1]
	v_pk_mul_f32 v[48:49], v[108:109], v[106:107] op_sel_hi:[0,1]
	v_pk_fma_f32 v[48:49], v[48:49], v[138:139], v[80:81]
	v_pk_fma_f32 v[50:51], v[50:51], v[136:137], v[78:79]
	v_mul_f32_e32 v53, v49, v49
	v_mul_f32_e32 v52, v51, v51
	v_fmac_f32_e32 v52, v50, v50
	v_fmac_f32_e32 v53, v48, v48
	v_add_f32_e32 v76, v52, v53
	v_pk_mul_f32 v[54:55], v[108:109], v[112:113] op_sel_hi:[0,1]
	v_pk_mul_f32 v[52:53], v[108:109], v[114:115] op_sel_hi:[0,1]
	v_pk_fma_f32 v[52:53], v[52:53], v[134:135], v[82:83]
	v_pk_fma_f32 v[54:55], v[54:55], v[132:133], v[110:111]
	v_mul_f32_e32 v78, v53, v53
	v_mul_f32_e32 v77, v55, v55
	v_fmac_f32_e32 v77, v54, v54
	v_fmac_f32_e32 v78, v52, v52
	v_add_f32_e32 v77, v77, v78
	v_add_f32_e32 v80, v76, v77
	v_pk_mul_f32 v[78:79], v[108:109], v[122:123] op_sel_hi:[0,1]
	v_pk_mul_f32 v[76:77], v[108:109], v[126:127] op_sel_hi:[0,1]
	v_pk_fma_f32 v[76:77], v[76:77], v[146:147], v[120:121]
	v_pk_fma_f32 v[78:79], v[78:79], v[144:145], v[118:119]
	v_mul_f32_e32 v82, v77, v77
	v_mul_f32_e32 v81, v79, v79
	v_fmac_f32_e32 v81, v78, v78
	v_fmac_f32_e32 v82, v76, v76
	v_add_f32_e32 v81, v81, v82
	v_add_f32_e32 v87, v80, v81
	v_pk_mul_f32 v[82:83], v[108:109], v[130:131] op_sel_hi:[0,1]
	v_pk_mul_f32 v[80:81], v[108:109], v[128:129] op_sel_hi:[0,1]
	v_pk_fma_f32 v[80:81], v[80:81], v[142:143], v[116:117]
	v_pk_fma_f32 v[82:83], v[82:83], v[140:141], v[124:125]
	v_mul_f32_e32 v89, v81, v81
	v_mul_f32_e32 v88, v83, v83
	v_fmac_f32_e32 v88, v82, v82
	v_fmac_f32_e32 v89, v80, v80
	v_add_f32_e32 v88, v88, v89
	v_add_f32_e32 v87, v87, v88
	s_nop 1
	v_add_f32_dpp v87, v87, v87 quad_perm:[1,0,3,2] row_mask:0xf bank_mask:0xf bound_ctrl:1
	s_nop 1
	v_add_f32_dpp v87, v87, v87 quad_perm:[2,3,0,1] row_mask:0xf bank_mask:0xf bound_ctrl:1
	s_nop 1
	v_add_f32_dpp v87, v87, v87 row_half_mirror row_mask:0xf bank_mask:0xf bound_ctrl:1
	s_nop 1
	v_add_f32_dpp v87, v87, v87 row_mirror row_mask:0xf bank_mask:0xf bound_ctrl:1
	s_nop 0
	v_readlane_b32 s1, v87, 16
	v_readlane_b32 s0, v87, 0
	s_nop 0
	v_mov_b32_e32 v88, s1
	v_readlane_b32 s1, v87, 48
	v_add_f32_e32 v88, s0, v88
	v_readlane_b32 s0, v87, 32
	v_mov_b32_e32 v87, s1
	s_nop 0
	v_add_f32_e32 v87, s0, v87
	v_add_f32_e32 v87, v88, v87
	v_fmamk_f32 v87, v87, 0x3a800000, v84
	s_and_saveexec_b64 s[4:5], s[6:7]
	s_cbranch_execz .LBB0_1161
	v_mul_f32_e32 v88, 0x4f800000, v87
	v_cmp_gt_f32_e32 vcc, s9, v87
	s_add_u32 s22, s92, s10
	s_addc_u32 s23, s93, s11
	v_cndmask_b32_e32 v88, v87, v88, vcc
	v_sqrt_f32_e32 v89, v88
	s_nop 0
	v_add_u32_e32 v90, -1, v89
	v_fma_f32 v91, -v90, v89, v88
	v_cmp_ge_f32_e64 s[0:1], 0, v91
	v_add_u32_e32 v91, 1, v89
	s_nop 0
	v_cndmask_b32_e64 v90, v89, v90, s[0:1]
	v_fma_f32 v89, -v91, v89, v88
	v_cmp_lt_f32_e64 s[0:1], 0, v89
	s_nop 1
	v_cndmask_b32_e64 v89, v90, v91, s[0:1]
	v_mul_f32_e32 v90, 0x37800000, v89
	v_cndmask_b32_e32 v89, v89, v90, vcc
	v_cmp_class_f32_e32 vcc, v88, v85
	s_nop 1
	v_cndmask_b32_e32 v88, v89, v88, vcc
	global_store_dword v86, v88, s[22:23]
.LBB0_1161:
	s_or_b64 exec, exec, s[4:5]
	v_rsq_f32_e32 v88, v87
	s_waitcnt vmcnt(17)
	v_lshlrev_b32_e32 v98, 16, v32
	v_and_b32_e32 v99, 0xffff0000, v32
	v_lshlrev_b32_e32 v100, 16, v33
	v_pk_mul_f32 v[90:91], v[88:89], v[48:49] op_sel_hi:[0,1]
	v_pk_mul_f32 v[48:49], v[88:89], v[50:51] op_sel_hi:[0,1]
	v_pk_mul_f32 v[52:53], v[88:89], v[52:53] op_sel_hi:[0,1]
	v_pk_mul_f32 v[50:51], v[88:89], v[54:55] op_sel_hi:[0,1]
	v_cvt_pk_bf16_f32 v48, v48, v49
	v_cvt_pk_bf16_f32 v49, v90, v91
	v_cvt_pk_bf16_f32 v50, v50, v51
	v_cvt_pk_bf16_f32 v51, v52, v53
	v_add_co_u32_e32 v52, vcc, s13, v62
	v_pk_mul_f32 v[54:55], v[88:89], v[76:77] op_sel_hi:[0,1]
	s_nop 0
	v_addc_co_u32_e32 v53, vcc, 0, v63, vcc
	v_pk_mul_f32 v[76:77], v[88:89], v[78:79] op_sel_hi:[0,1]
	v_pk_mul_f32 v[78:79], v[88:89], v[80:81] op_sel_hi:[0,1]
	v_pk_mul_f32 v[80:81], v[88:89], v[82:83] op_sel_hi:[0,1]
	global_store_dwordx4 v[52:53], v[48:51], off
	s_waitcnt vmcnt(15)
	v_lshlrev_b32_e32 v88, 16, v42
	v_and_b32_e32 v89, 0xffff0000, v42
	v_cvt_pk_bf16_f32 v48, v76, v77
	v_cvt_pk_bf16_f32 v49, v54, v55
	v_cvt_pk_bf16_f32 v50, v80, v81
	v_cvt_pk_bf16_f32 v51, v78, v79
	global_store_dwordx4 v[52:53], v[48:51], off offset:1024
	v_cvt_f32_ubyte3_e32 v53, v74
	v_cvt_f32_ubyte2_e32 v52, v74
	v_cvt_f32_ubyte1_e32 v51, v74
	v_cvt_f32_ubyte0_e32 v50, v74
	v_pk_mul_f32 v[52:53], v[52:53], s[12:13] op_sel_hi:[1,0]
	v_pk_mul_f32 v[50:51], v[50:51], s[12:13] op_sel_hi:[1,0]
	v_lshlrev_b32_e32 v54, 16, v40
	v_and_b32_e32 v55, 0xffff0000, v40
	v_lshlrev_b32_e32 v40, 16, v41
	v_and_b32_e32 v41, 0xffff0000, v41
	v_pk_mul_f32 v[54:55], v[50:51], v[54:55]
	v_pk_mul_f32 v[40:41], v[52:53], v[40:41]
	v_pk_mul_f32 v[52:53], v[54:55], v[54:55]
	v_pk_mul_f32 v[50:51], v[40:41], v[40:41]
	v_lshlrev_b32_e32 v42, 16, v43
	v_pk_mov_b32 v[76:77], v[52:53], v[50:51] op_sel:[1,0]
	v_mov_b32_e32 v53, v51
	v_pk_add_f32 v[82:83], v[76:77], v[52:53]
	v_cvt_f32_ubyte1_e32 v51, v75
	v_cvt_f32_ubyte0_e32 v50, v75
	v_cvt_f32_ubyte3_e32 v53, v75
	v_cvt_f32_ubyte2_e32 v52, v75
	v_pk_mul_f32 v[78:79], v[52:53], s[12:13] op_sel_hi:[1,0]
	v_pk_mul_f32 v[80:81], v[50:51], s[12:13] op_sel_hi:[1,0]
	v_and_b32_e32 v43, 0xffff0000, v43
	v_pk_mul_f32 v[94:95], v[80:81], v[88:89]
	v_pk_mul_f32 v[42:43], v[78:79], v[42:43]
	v_pk_mul_f32 v[80:81], v[94:95], v[94:95]
	v_pk_mul_f32 v[78:79], v[42:43], v[42:43]
	v_and_b32_e32 v101, 0xffff0000, v33
	v_pk_mov_b32 v[88:89], v[80:81], v[78:79] op_sel:[1,0]
	v_mov_b32_e32 v81, v79
	v_pk_add_f32 v[96:97], v[88:89], v[80:81]
	v_cvt_f32_ubyte3_e32 v33, v72
	v_cvt_f32_ubyte2_e32 v32, v72
	v_cvt_f32_ubyte1_e32 v103, v72
	v_cvt_f32_ubyte0_e32 v102, v72
	v_pk_mul_f32 v[32:33], v[32:33], s[12:13] op_sel_hi:[1,0]
	s_waitcnt vmcnt(15)
	v_lshlrev_b32_e32 v104, 16, v36
	v_and_b32_e32 v105, 0xffff0000, v36
	v_lshlrev_b32_e32 v36, 16, v37
	v_and_b32_e32 v37, 0xffff0000, v37
	v_pk_mul_f32 v[102:103], v[102:103], s[12:13] op_sel_hi:[1,0]
	v_pk_mul_f32 v[106:107], v[32:33], v[36:37]
	v_cvt_f32_ubyte1_e32 v37, v73
	v_cvt_f32_ubyte0_e32 v36, v73
	v_pk_mul_f32 v[102:103], v[102:103], v[104:105]
	v_cvt_f32_ubyte3_e32 v33, v73
	v_cvt_f32_ubyte2_e32 v32, v73
	v_pk_mul_f32 v[36:37], v[36:37], s[12:13] op_sel_hi:[1,0]
	v_lshlrev_b32_e32 v104, 16, v38
	v_and_b32_e32 v105, 0xffff0000, v38
	v_pk_mul_f32 v[32:33], v[32:33], s[12:13] op_sel_hi:[1,0]
	v_lshlrev_b32_e32 v38, 16, v39
	v_and_b32_e32 v39, 0xffff0000, v39
	v_pk_mul_f32 v[104:105], v[36:37], v[104:105]
	v_pk_mul_f32 v[108:109], v[32:33], v[38:39]
	v_mul_f32_e32 v36, v104, v104
	v_pk_add_f32 v[32:33], v[82:83], v[82:83] op_sel:[0,1] op_sel_hi:[1,0]
	v_mul_f32_e32 v38, v105, v105
	v_mov_b32_e32 v33, v36
	v_pk_add_f32 v[36:37], v[96:97], v[96:97] op_sel:[0,1] op_sel_hi:[1,0]
	v_mul_f32_e32 v39, v108, v108
	v_mov_b32_e32 v37, v38
	v_pk_add_f32 v[32:33], v[32:33], v[36:37]
	v_mul_f32_e32 v36, v103, v103
	v_pk_fma_f32 v[36:37], v[102:103], v[102:103], v[36:37] op_sel_hi:[1,1,0]
	v_mul_f32_e32 v38, v107, v107
	v_mul_f32_e32 v73, v109, v109
	v_mov_b32_e32 v37, v39
	v_pk_fma_f32 v[38:39], v[106:107], v[106:107], v[38:39] op_sel_hi:[1,1,0]
	v_lshlrev_b32_e32 v48, 16, v44
	v_mov_b32_e32 v39, v73
	v_pk_add_f32 v[36:37], v[36:37], v[38:39]
	v_and_b32_e32 v49, 0xffff0000, v44
	v_pk_add_f32 v[32:33], v[32:33], v[36:37]
	v_lshlrev_b32_e32 v44, 16, v45
	v_add_f32_e32 v32, v32, v33
	v_and_b32_e32 v45, 0xffff0000, v45
	v_lshlrev_b32_e32 v72, 16, v34
	v_add_f32_dpp v32, v32, v32 quad_perm:[1,0,3,2] row_mask:0xf bank_mask:0xf bound_ctrl:1
	v_and_b32_e32 v73, 0xffff0000, v34
	v_lshlrev_b32_e32 v96, 16, v35
	v_add_f32_dpp v32, v32, v32 quad_perm:[2,3,0,1] row_mask:0xf bank_mask:0xf bound_ctrl:1
	v_and_b32_e32 v97, 0xffff0000, v35
	v_lshlrev_b32_e32 v92, 16, v46
	v_add_f32_dpp v32, v32, v32 row_half_mirror row_mask:0xf bank_mask:0xf bound_ctrl:1
	v_and_b32_e32 v93, 0xffff0000, v46
	v_lshlrev_b32_e32 v46, 16, v47
	v_add_f32_dpp v32, v32, v32 row_mirror row_mask:0xf bank_mask:0xf bound_ctrl:1
	v_and_b32_e32 v47, 0xffff0000, v47
	v_readlane_b32 s4, v32, 16
	v_readlane_b32 s5, v32, 48
	v_readlane_b32 s0, v32, 0
	v_readlane_b32 s1, v32, 32
	v_mov_b32_e32 v32, s4
	v_mov_b32_e32 v33, s5
	v_pk_add_f32 v[32:33], s[0:1], v[32:33]
	s_nop 0
	v_add_f32_e32 v32, v32, v33
	v_fmamk_f32 v32, v32, 0x3a800000, v84
	v_rsq_f32_e32 v82, v32
	s_nop 0
	v_pk_mul_f32 v[34:35], v[82:83], v[54:55] op_sel_hi:[0,1]
	v_pk_mul_f32 v[32:33], v[82:83], v[40:41] op_sel_hi:[0,1]
	v_pk_fma_f32 v[32:33], v[32:33], v[138:139], v[44:45]
	v_pk_fma_f32 v[34:35], v[34:35], v[136:137], v[48:49]
	v_mul_f32_e32 v37, v33, v33
	v_mul_f32_e32 v36, v35, v35
	v_fmac_f32_e32 v36, v34, v34
	v_fmac_f32_e32 v37, v32, v32
	v_add_f32_e32 v40, v36, v37
	v_pk_mul_f32 v[38:39], v[82:83], v[94:95] op_sel_hi:[0,1]
	v_pk_mul_f32 v[36:37], v[82:83], v[42:43] op_sel_hi:[0,1]
	v_pk_fma_f32 v[36:37], v[36:37], v[134:135], v[46:47]
	v_pk_fma_f32 v[38:39], v[38:39], v[132:133], v[92:93]
	v_mul_f32_e32 v42, v37, v37
	v_mul_f32_e32 v41, v39, v39
	v_fmac_f32_e32 v41, v38, v38
	v_fmac_f32_e32 v42, v36, v36
	v_add_f32_e32 v41, v41, v42
	v_add_f32_e32 v44, v40, v41
	v_pk_mul_f32 v[42:43], v[82:83], v[102:103] op_sel_hi:[0,1]
	v_pk_mul_f32 v[40:41], v[82:83], v[106:107] op_sel_hi:[0,1]
	v_pk_fma_f32 v[40:41], v[40:41], v[146:147], v[100:101]
	v_pk_fma_f32 v[42:43], v[42:43], v[144:145], v[98:99]
	v_mul_f32_e32 v46, v41, v41
	v_mul_f32_e32 v45, v43, v43
	v_fmac_f32_e32 v45, v42, v42
	v_fmac_f32_e32 v46, v40, v40
	v_add_f32_e32 v45, v45, v46
	v_add_f32_e32 v48, v44, v45
	v_pk_mul_f32 v[46:47], v[82:83], v[104:105] op_sel_hi:[0,1]
	v_pk_mul_f32 v[44:45], v[82:83], v[108:109] op_sel_hi:[0,1]
	v_pk_fma_f32 v[44:45], v[44:45], v[142:143], v[96:97]
	v_pk_fma_f32 v[46:47], v[46:47], v[140:141], v[72:73]
	v_mul_f32_e32 v50, v45, v45
	v_mul_f32_e32 v49, v47, v47
	v_fmac_f32_e32 v49, v46, v46
	v_fmac_f32_e32 v50, v44, v44
	v_add_f32_e32 v49, v49, v50
	v_add_f32_e32 v48, v48, v49
	s_nop 1
	v_add_f32_dpp v48, v48, v48 quad_perm:[1,0,3,2] row_mask:0xf bank_mask:0xf bound_ctrl:1
	s_nop 1
	v_add_f32_dpp v48, v48, v48 quad_perm:[2,3,0,1] row_mask:0xf bank_mask:0xf bound_ctrl:1
	s_nop 1
	v_add_f32_dpp v48, v48, v48 row_half_mirror row_mask:0xf bank_mask:0xf bound_ctrl:1
	s_nop 1
	v_add_f32_dpp v48, v48, v48 row_mirror row_mask:0xf bank_mask:0xf bound_ctrl:1
	s_nop 0
	v_readlane_b32 s1, v48, 16
	v_readlane_b32 s0, v48, 0
	s_nop 0
	v_mov_b32_e32 v49, s1
	v_readlane_b32 s1, v48, 48
	v_add_f32_e32 v49, s0, v49
	v_readlane_b32 s0, v48, 32
	v_mov_b32_e32 v48, s1
	s_nop 0
	v_add_f32_e32 v48, s0, v48
	v_add_f32_e32 v48, v49, v48
	v_fmamk_f32 v48, v48, 0x3a800000, v84
	s_and_saveexec_b64 s[4:5], s[6:7]
	s_cbranch_execz .LBB0_1163
	v_mul_f32_e32 v49, 0x4f800000, v48
	v_cmp_gt_f32_e32 vcc, s9, v48
	s_add_u32 s22, s92, s10
	s_addc_u32 s23, s93, s11
	v_cndmask_b32_e32 v49, v48, v49, vcc
	v_sqrt_f32_e32 v50, v49
	s_nop 0
	v_add_u32_e32 v51, -1, v50
	v_fma_f32 v52, -v51, v50, v49
	v_cmp_ge_f32_e64 s[0:1], 0, v52
	v_add_u32_e32 v52, 1, v50
	s_nop 0
	v_cndmask_b32_e64 v51, v50, v51, s[0:1]
	v_fma_f32 v50, -v52, v50, v49
	v_cmp_lt_f32_e64 s[0:1], 0, v50
	s_nop 1
	v_cndmask_b32_e64 v50, v51, v52, s[0:1]
	v_mul_f32_e32 v51, 0x37800000, v50
	v_cndmask_b32_e32 v50, v50, v51, vcc
	v_cmp_class_f32_e32 vcc, v49, v85
	s_nop 1
	v_cndmask_b32_e32 v49, v50, v49, vcc
	global_store_dword v86, v49, s[22:23] offset:1024
.LBB0_1163:
	s_or_b64 exec, exec, s[4:5]
	v_rsq_f32_e32 v48, v48
	s_waitcnt vmcnt(14)
	v_lshlrev_b32_e32 v74, 16, v16
	v_and_b32_e32 v75, 0xffff0000, v16
	v_lshlrev_b32_e32 v76, 16, v17
	v_pk_mul_f32 v[50:51], v[48:49], v[32:33] op_sel_hi:[0,1]
	v_pk_mul_f32 v[32:33], v[48:49], v[34:35] op_sel_hi:[0,1]
	v_pk_mul_f32 v[36:37], v[48:49], v[36:37] op_sel_hi:[0,1]
	v_pk_mul_f32 v[34:35], v[48:49], v[38:39] op_sel_hi:[0,1]
	v_cvt_pk_bf16_f32 v32, v32, v33
	v_cvt_pk_bf16_f32 v33, v50, v51
	v_cvt_pk_bf16_f32 v34, v34, v35
	v_cvt_pk_bf16_f32 v35, v36, v37
	v_add_co_u32_e32 v36, vcc, s18, v62
	v_pk_mul_f32 v[38:39], v[48:49], v[40:41] op_sel_hi:[0,1]
	s_nop 0
	v_addc_co_u32_e32 v37, vcc, 0, v63, vcc
	v_pk_mul_f32 v[40:41], v[48:49], v[42:43] op_sel_hi:[0,1]
	v_pk_mul_f32 v[42:43], v[48:49], v[44:45] op_sel_hi:[0,1]
	v_pk_mul_f32 v[44:45], v[48:49], v[46:47] op_sel_hi:[0,1]
	global_store_dwordx4 v[36:37], v[32:35], off
	s_waitcnt vmcnt(12)
	v_lshlrev_b32_e32 v46, 16, v26
	v_and_b32_e32 v47, 0xffff0000, v26
	v_cvt_pk_bf16_f32 v32, v40, v41
	v_cvt_pk_bf16_f32 v33, v38, v39
	v_cvt_pk_bf16_f32 v34, v44, v45
	v_cvt_pk_bf16_f32 v35, v42, v43
	global_store_dwordx4 v[36:37], v[32:35], off offset:1024
	v_cvt_f32_ubyte3_e32 v37, v70
	v_cvt_f32_ubyte2_e32 v36, v70
	v_cvt_f32_ubyte1_e32 v35, v70
	v_cvt_f32_ubyte0_e32 v34, v70
	v_pk_mul_f32 v[36:37], v[36:37], s[12:13] op_sel_hi:[1,0]
	v_pk_mul_f32 v[34:35], v[34:35], s[12:13] op_sel_hi:[1,0]
	v_lshlrev_b32_e32 v38, 16, v24
	v_and_b32_e32 v39, 0xffff0000, v24
	v_lshlrev_b32_e32 v24, 16, v25
	v_and_b32_e32 v25, 0xffff0000, v25
	v_pk_mul_f32 v[50:51], v[34:35], v[38:39]
	v_pk_mul_f32 v[24:25], v[36:37], v[24:25]
	v_pk_mul_f32 v[36:37], v[50:51], v[50:51]
	v_pk_mul_f32 v[34:35], v[24:25], v[24:25]
	v_lshlrev_b32_e32 v26, 16, v27
	v_pk_mov_b32 v[38:39], v[36:37], v[34:35] op_sel:[1,0]
	v_mov_b32_e32 v37, v35
	v_pk_add_f32 v[52:53], v[38:39], v[36:37]
	v_cvt_f32_ubyte1_e32 v35, v71
	v_cvt_f32_ubyte0_e32 v34, v71
	v_cvt_f32_ubyte3_e32 v37, v71
	v_cvt_f32_ubyte2_e32 v36, v71
	v_pk_mul_f32 v[42:43], v[36:37], s[12:13] op_sel_hi:[1,0]
	v_pk_mul_f32 v[44:45], v[34:35], s[12:13] op_sel_hi:[1,0]
	v_and_b32_e32 v27, 0xffff0000, v27
	v_pk_mul_f32 v[70:71], v[44:45], v[46:47]
	v_pk_mul_f32 v[26:27], v[42:43], v[26:27]
	v_pk_mul_f32 v[44:45], v[70:71], v[70:71]
	v_pk_mul_f32 v[42:43], v[26:27], v[26:27]
	v_and_b32_e32 v77, 0xffff0000, v17
	v_pk_mov_b32 v[46:47], v[44:45], v[42:43] op_sel:[1,0]
	v_mov_b32_e32 v45, v43
	v_pk_add_f32 v[72:73], v[46:47], v[44:45]
	v_cvt_f32_ubyte3_e32 v17, v68
	v_cvt_f32_ubyte2_e32 v16, v68
	v_cvt_f32_ubyte1_e32 v79, v68
	v_cvt_f32_ubyte0_e32 v78, v68
	v_pk_mul_f32 v[16:17], v[16:17], s[12:13] op_sel_hi:[1,0]
	s_waitcnt vmcnt(12)
	v_lshlrev_b32_e32 v80, 16, v20
	v_and_b32_e32 v81, 0xffff0000, v20
	v_lshlrev_b32_e32 v20, 16, v21
	v_and_b32_e32 v21, 0xffff0000, v21
	v_pk_mul_f32 v[78:79], v[78:79], s[12:13] op_sel_hi:[1,0]
	v_pk_mul_f32 v[82:83], v[16:17], v[20:21]
	v_cvt_f32_ubyte1_e32 v21, v69
	v_cvt_f32_ubyte0_e32 v20, v69
	v_pk_mul_f32 v[78:79], v[78:79], v[80:81]
	v_cvt_f32_ubyte3_e32 v17, v69
	v_cvt_f32_ubyte2_e32 v16, v69
	v_pk_mul_f32 v[20:21], v[20:21], s[12:13] op_sel_hi:[1,0]
	v_lshlrev_b32_e32 v80, 16, v22
	v_and_b32_e32 v81, 0xffff0000, v22
	v_pk_mul_f32 v[16:17], v[16:17], s[12:13] op_sel_hi:[1,0]
	v_lshlrev_b32_e32 v22, 16, v23
	v_and_b32_e32 v23, 0xffff0000, v23
	v_pk_mul_f32 v[80:81], v[20:21], v[80:81]
	v_pk_mul_f32 v[88:89], v[16:17], v[22:23]
	v_mul_f32_e32 v20, v80, v80
	v_pk_add_f32 v[16:17], v[52:53], v[52:53] op_sel:[0,1] op_sel_hi:[1,0]
	v_mul_f32_e32 v22, v81, v81
	v_mov_b32_e32 v17, v20
	v_pk_add_f32 v[20:21], v[72:73], v[72:73] op_sel:[0,1] op_sel_hi:[1,0]
	v_mul_f32_e32 v23, v88, v88
	v_mov_b32_e32 v21, v22
	v_pk_add_f32 v[16:17], v[16:17], v[20:21]
	v_mul_f32_e32 v20, v79, v79
	v_pk_fma_f32 v[20:21], v[78:79], v[78:79], v[20:21] op_sel_hi:[1,1,0]
	v_mul_f32_e32 v22, v83, v83
	v_mul_f32_e32 v69, v89, v89
	v_mov_b32_e32 v21, v23
	v_pk_fma_f32 v[22:23], v[82:83], v[82:83], v[22:23] op_sel_hi:[1,1,0]
	v_lshlrev_b32_e32 v32, 16, v28
	v_mov_b32_e32 v23, v69
	v_pk_add_f32 v[20:21], v[20:21], v[22:23]
	v_and_b32_e32 v33, 0xffff0000, v28
	v_pk_add_f32 v[16:17], v[16:17], v[20:21]
	v_lshlrev_b32_e32 v28, 16, v29
	v_add_f32_e32 v16, v16, v17
	v_and_b32_e32 v29, 0xffff0000, v29
	v_lshlrev_b32_e32 v68, 16, v18
	v_add_f32_dpp v16, v16, v16 quad_perm:[1,0,3,2] row_mask:0xf bank_mask:0xf bound_ctrl:1
	v_and_b32_e32 v69, 0xffff0000, v18
	v_lshlrev_b32_e32 v72, 16, v19
	v_add_f32_dpp v16, v16, v16 quad_perm:[2,3,0,1] row_mask:0xf bank_mask:0xf bound_ctrl:1
	v_and_b32_e32 v73, 0xffff0000, v19
	v_lshlrev_b32_e32 v54, 16, v30
	v_add_f32_dpp v16, v16, v16 row_half_mirror row_mask:0xf bank_mask:0xf bound_ctrl:1
	v_and_b32_e32 v55, 0xffff0000, v30
	v_lshlrev_b32_e32 v30, 16, v31
	v_add_f32_dpp v16, v16, v16 row_mirror row_mask:0xf bank_mask:0xf bound_ctrl:1
	v_and_b32_e32 v31, 0xffff0000, v31
	v_readlane_b32 s4, v16, 16
	v_readlane_b32 s5, v16, 48
	v_readlane_b32 s0, v16, 0
	v_readlane_b32 s1, v16, 32
	v_mov_b32_e32 v16, s4
	v_mov_b32_e32 v17, s5
	v_pk_add_f32 v[16:17], s[0:1], v[16:17]
	s_nop 0
	v_add_f32_e32 v16, v16, v17
	v_fmamk_f32 v16, v16, 0x3a800000, v84
	v_rsq_f32_e32 v52, v16
	s_nop 0
	v_pk_mul_f32 v[18:19], v[52:53], v[50:51] op_sel_hi:[0,1]
	v_pk_mul_f32 v[16:17], v[52:53], v[24:25] op_sel_hi:[0,1]
	v_pk_fma_f32 v[16:17], v[16:17], v[138:139], v[28:29]
	v_pk_fma_f32 v[18:19], v[18:19], v[136:137], v[32:33]
	v_mul_f32_e32 v21, v17, v17
	v_mul_f32_e32 v20, v19, v19
	v_fmac_f32_e32 v20, v18, v18
	v_fmac_f32_e32 v21, v16, v16
	v_add_f32_e32 v24, v20, v21
	v_pk_mul_f32 v[22:23], v[52:53], v[70:71] op_sel_hi:[0,1]
	v_pk_mul_f32 v[20:21], v[52:53], v[26:27] op_sel_hi:[0,1]
	v_pk_fma_f32 v[20:21], v[20:21], v[134:135], v[30:31]
	v_pk_fma_f32 v[22:23], v[22:23], v[132:133], v[54:55]
	v_mul_f32_e32 v26, v21, v21
	v_mul_f32_e32 v25, v23, v23
	v_fmac_f32_e32 v25, v22, v22
	v_fmac_f32_e32 v26, v20, v20
	v_add_f32_e32 v25, v25, v26
	v_add_f32_e32 v28, v24, v25
	v_pk_mul_f32 v[26:27], v[52:53], v[78:79] op_sel_hi:[0,1]
	v_pk_mul_f32 v[24:25], v[52:53], v[82:83] op_sel_hi:[0,1]
	v_pk_fma_f32 v[24:25], v[24:25], v[146:147], v[76:77]
	v_pk_fma_f32 v[26:27], v[26:27], v[144:145], v[74:75]
	v_mul_f32_e32 v30, v25, v25
	v_mul_f32_e32 v29, v27, v27
	v_fmac_f32_e32 v29, v26, v26
	v_fmac_f32_e32 v30, v24, v24
	v_add_f32_e32 v29, v29, v30
	v_add_f32_e32 v32, v28, v29
	v_pk_mul_f32 v[30:31], v[52:53], v[80:81] op_sel_hi:[0,1]
	v_pk_mul_f32 v[28:29], v[52:53], v[88:89] op_sel_hi:[0,1]
	v_pk_fma_f32 v[28:29], v[28:29], v[142:143], v[72:73]
	v_pk_fma_f32 v[30:31], v[30:31], v[140:141], v[68:69]
	v_mul_f32_e32 v34, v29, v29
	v_mul_f32_e32 v33, v31, v31
	v_fmac_f32_e32 v33, v30, v30
	v_fmac_f32_e32 v34, v28, v28
	v_add_f32_e32 v33, v33, v34
	v_add_f32_e32 v32, v32, v33
	s_nop 1
	v_add_f32_dpp v32, v32, v32 quad_perm:[1,0,3,2] row_mask:0xf bank_mask:0xf bound_ctrl:1
	s_nop 1
	v_add_f32_dpp v32, v32, v32 quad_perm:[2,3,0,1] row_mask:0xf bank_mask:0xf bound_ctrl:1
	s_nop 1
	v_add_f32_dpp v32, v32, v32 row_half_mirror row_mask:0xf bank_mask:0xf bound_ctrl:1
	s_nop 1
	v_add_f32_dpp v32, v32, v32 row_mirror row_mask:0xf bank_mask:0xf bound_ctrl:1
	s_nop 0
	v_readlane_b32 s1, v32, 16
	v_readlane_b32 s0, v32, 0
	s_nop 0
	v_mov_b32_e32 v33, s1
	v_readlane_b32 s1, v32, 48
	v_add_f32_e32 v33, s0, v33
	v_readlane_b32 s0, v32, 32
	v_mov_b32_e32 v32, s1
	s_nop 0
	v_add_f32_e32 v32, s0, v32
	v_add_f32_e32 v32, v33, v32
	v_fmamk_f32 v32, v32, 0x3a800000, v84
	s_and_saveexec_b64 s[4:5], s[6:7]
	s_cbranch_execz .LBB0_1165
	v_mul_f32_e32 v33, 0x4f800000, v32
	v_cmp_gt_f32_e32 vcc, s9, v32
	s_add_u32 s22, s92, s10
	s_addc_u32 s23, s93, s11
	v_cndmask_b32_e32 v33, v32, v33, vcc
	v_sqrt_f32_e32 v34, v33
	s_nop 0
	v_add_u32_e32 v35, -1, v34
	v_fma_f32 v36, -v35, v34, v33
	v_cmp_ge_f32_e64 s[0:1], 0, v36
	v_add_u32_e32 v36, 1, v34
	s_nop 0
	v_cndmask_b32_e64 v35, v34, v35, s[0:1]
	v_fma_f32 v34, -v36, v34, v33
	v_cmp_lt_f32_e64 s[0:1], 0, v34
	s_nop 1
	v_cndmask_b32_e64 v34, v35, v36, s[0:1]
	v_mul_f32_e32 v35, 0x37800000, v34
	v_cndmask_b32_e32 v34, v34, v35, vcc
	v_cmp_class_f32_e32 vcc, v33, v85
	s_nop 1
	v_cndmask_b32_e32 v33, v34, v33, vcc
	global_store_dword v86, v33, s[22:23] offset:2048
.LBB0_1165:
	s_or_b64 exec, exec, s[4:5]
	v_rsq_f32_e32 v32, v32
	s_waitcnt vmcnt(11)
	v_lshlrev_b32_e32 v44, 16, v0
	v_and_b32_e32 v45, 0xffff0000, v0
	v_lshlrev_b32_e32 v46, 16, v1
	v_pk_mul_f32 v[34:35], v[32:33], v[16:17] op_sel_hi:[0,1]
	v_pk_mul_f32 v[16:17], v[32:33], v[18:19] op_sel_hi:[0,1]
	v_pk_mul_f32 v[20:21], v[32:33], v[20:21] op_sel_hi:[0,1]
	v_pk_mul_f32 v[18:19], v[32:33], v[22:23] op_sel_hi:[0,1]
	v_cvt_pk_bf16_f32 v16, v16, v17
	v_cvt_pk_bf16_f32 v17, v34, v35
	v_cvt_pk_bf16_f32 v18, v18, v19
	v_cvt_pk_bf16_f32 v19, v20, v21
	v_add_co_u32_e32 v20, vcc, s19, v62
	v_pk_mul_f32 v[22:23], v[32:33], v[24:25] op_sel_hi:[0,1]
	s_nop 0
	v_addc_co_u32_e32 v21, vcc, 0, v63, vcc
	v_pk_mul_f32 v[24:25], v[32:33], v[26:27] op_sel_hi:[0,1]
	v_pk_mul_f32 v[26:27], v[32:33], v[28:29] op_sel_hi:[0,1]
	v_pk_mul_f32 v[28:29], v[32:33], v[30:31] op_sel_hi:[0,1]
	global_store_dwordx4 v[20:21], v[16:19], off
	s_waitcnt vmcnt(9)
	v_lshlrev_b32_e32 v30, 16, v10
	v_and_b32_e32 v31, 0xffff0000, v10
	v_cvt_pk_bf16_f32 v16, v24, v25
	v_cvt_pk_bf16_f32 v17, v22, v23
	v_cvt_pk_bf16_f32 v18, v28, v29
	v_cvt_pk_bf16_f32 v19, v26, v27
	global_store_dwordx4 v[20:21], v[16:19], off offset:1024
	v_cvt_f32_ubyte3_e32 v21, v66
	v_cvt_f32_ubyte2_e32 v20, v66
	v_cvt_f32_ubyte1_e32 v19, v66
	v_cvt_f32_ubyte0_e32 v18, v66
	v_pk_mul_f32 v[20:21], v[20:21], s[12:13] op_sel_hi:[1,0]
	v_pk_mul_f32 v[18:19], v[18:19], s[12:13] op_sel_hi:[1,0]
	v_lshlrev_b32_e32 v22, 16, v8
	v_and_b32_e32 v23, 0xffff0000, v8
	v_lshlrev_b32_e32 v8, 16, v9
	v_and_b32_e32 v9, 0xffff0000, v9
	v_pk_mul_f32 v[34:35], v[18:19], v[22:23]
	v_pk_mul_f32 v[8:9], v[20:21], v[8:9]
	v_pk_mul_f32 v[20:21], v[34:35], v[34:35]
	v_pk_mul_f32 v[18:19], v[8:9], v[8:9]
	v_lshlrev_b32_e32 v10, 16, v11
	v_pk_mov_b32 v[22:23], v[20:21], v[18:19] op_sel:[1,0]
	v_mov_b32_e32 v21, v19
	v_pk_add_f32 v[36:37], v[22:23], v[20:21]
	v_cvt_f32_ubyte1_e32 v19, v67
	v_cvt_f32_ubyte0_e32 v18, v67
	v_cvt_f32_ubyte3_e32 v21, v67
	v_cvt_f32_ubyte2_e32 v20, v67
	v_pk_mul_f32 v[26:27], v[20:21], s[12:13] op_sel_hi:[1,0]
	v_pk_mul_f32 v[28:29], v[18:19], s[12:13] op_sel_hi:[1,0]
	v_and_b32_e32 v11, 0xffff0000, v11
	v_pk_mul_f32 v[40:41], v[28:29], v[30:31]
	v_pk_mul_f32 v[10:11], v[26:27], v[10:11]
	v_pk_mul_f32 v[28:29], v[40:41], v[40:41]
	v_pk_mul_f32 v[26:27], v[10:11], v[10:11]
	v_and_b32_e32 v47, 0xffff0000, v1
	v_pk_mov_b32 v[30:31], v[28:29], v[26:27] op_sel:[1,0]
	v_mov_b32_e32 v29, v27
	v_pk_add_f32 v[42:43], v[30:31], v[28:29]
	v_cvt_f32_ubyte3_e32 v1, v64
	v_cvt_f32_ubyte2_e32 v0, v64
	v_pk_mul_f32 v[0:1], v[0:1], s[12:13] op_sel_hi:[1,0]
	s_waitcnt vmcnt(9)
	v_lshlrev_b32_e32 v50, 16, v4
	v_and_b32_e32 v51, 0xffff0000, v4
	v_lshlrev_b32_e32 v4, 16, v5
	v_and_b32_e32 v5, 0xffff0000, v5
	v_pk_mul_f32 v[52:53], v[0:1], v[4:5]
	v_cvt_f32_ubyte1_e32 v5, v65
	v_cvt_f32_ubyte0_e32 v4, v65
	v_cvt_f32_ubyte3_e32 v1, v65
	v_cvt_f32_ubyte2_e32 v0, v65
	v_pk_mul_f32 v[4:5], v[4:5], s[12:13] op_sel_hi:[1,0]
	v_lshlrev_b32_e32 v54, 16, v6
	v_and_b32_e32 v55, 0xffff0000, v6
	v_pk_mul_f32 v[0:1], v[0:1], s[12:13] op_sel_hi:[1,0]
	v_lshlrev_b32_e32 v6, 16, v7
	v_and_b32_e32 v7, 0xffff0000, v7
	v_pk_mul_f32 v[54:55], v[4:5], v[54:55]
	v_cvt_f32_ubyte1_e32 v49, v64
	v_cvt_f32_ubyte0_e32 v48, v64
	v_pk_mul_f32 v[64:65], v[0:1], v[6:7]
	v_mul_f32_e32 v4, v54, v54
	v_pk_add_f32 v[0:1], v[36:37], v[36:37] op_sel:[0,1] op_sel_hi:[1,0]
	v_pk_mul_f32 v[48:49], v[48:49], s[12:13] op_sel_hi:[1,0]
	v_mul_f32_e32 v6, v55, v55
	v_mov_b32_e32 v1, v4
	v_pk_add_f32 v[4:5], v[42:43], v[42:43] op_sel:[0,1] op_sel_hi:[1,0]
	v_pk_mul_f32 v[48:49], v[48:49], v[50:51]
	v_mov_b32_e32 v5, v6
	v_pk_add_f32 v[0:1], v[0:1], v[4:5]
	v_mul_f32_e32 v4, v49, v49
	v_mul_f32_e32 v7, v64, v64
	v_pk_fma_f32 v[4:5], v[48:49], v[48:49], v[4:5] op_sel_hi:[1,1,0]
	v_mul_f32_e32 v6, v53, v53
	v_mul_f32_e32 v51, v65, v65
	v_mov_b32_e32 v5, v7
	v_pk_fma_f32 v[6:7], v[52:53], v[52:53], v[6:7] op_sel_hi:[1,1,0]
	v_lshlrev_b32_e32 v16, 16, v12
	v_mov_b32_e32 v7, v51
	v_pk_add_f32 v[4:5], v[4:5], v[6:7]
	v_and_b32_e32 v17, 0xffff0000, v12
	v_pk_add_f32 v[0:1], v[0:1], v[4:5]
	v_lshlrev_b32_e32 v12, 16, v13
	v_add_f32_e32 v0, v0, v1
	v_and_b32_e32 v13, 0xffff0000, v13
	v_lshlrev_b32_e32 v50, 16, v2
	v_add_f32_dpp v0, v0, v0 quad_perm:[1,0,3,2] row_mask:0xf bank_mask:0xf bound_ctrl:1
	v_and_b32_e32 v51, 0xffff0000, v2
	v_lshlrev_b32_e32 v42, 16, v3
	v_add_f32_dpp v0, v0, v0 quad_perm:[2,3,0,1] row_mask:0xf bank_mask:0xf bound_ctrl:1
	v_and_b32_e32 v43, 0xffff0000, v3
	v_lshlrev_b32_e32 v38, 16, v14
	v_add_f32_dpp v0, v0, v0 row_half_mirror row_mask:0xf bank_mask:0xf bound_ctrl:1
	v_and_b32_e32 v39, 0xffff0000, v14
	v_lshlrev_b32_e32 v14, 16, v15
	v_add_f32_dpp v0, v0, v0 row_mirror row_mask:0xf bank_mask:0xf bound_ctrl:1
	v_and_b32_e32 v15, 0xffff0000, v15
	v_readlane_b32 s4, v0, 16
	v_readlane_b32 s5, v0, 48
	v_readlane_b32 s0, v0, 0
	v_readlane_b32 s1, v0, 32
	v_mov_b32_e32 v0, s4
	v_mov_b32_e32 v1, s5
	v_pk_add_f32 v[0:1], s[0:1], v[0:1]
	s_nop 0
	v_add_f32_e32 v0, v0, v1
	v_fmamk_f32 v0, v0, 0x3a800000, v84
	v_rsq_f32_e32 v36, v0
	s_nop 0
	v_pk_mul_f32 v[2:3], v[36:37], v[34:35] op_sel_hi:[0,1]
	v_pk_mul_f32 v[0:1], v[36:37], v[8:9] op_sel_hi:[0,1]
	v_pk_fma_f32 v[0:1], v[0:1], v[138:139], v[12:13]
	v_pk_fma_f32 v[2:3], v[2:3], v[136:137], v[16:17]
	v_mul_f32_e32 v5, v1, v1
	v_mul_f32_e32 v4, v3, v3
	v_fmac_f32_e32 v4, v2, v2
	v_fmac_f32_e32 v5, v0, v0
	v_add_f32_e32 v8, v4, v5
	v_pk_mul_f32 v[6:7], v[36:37], v[40:41] op_sel_hi:[0,1]
	v_pk_mul_f32 v[4:5], v[36:37], v[10:11] op_sel_hi:[0,1]
	v_pk_fma_f32 v[4:5], v[4:5], v[134:135], v[14:15]
	v_pk_fma_f32 v[6:7], v[6:7], v[132:133], v[38:39]
	v_mul_f32_e32 v10, v5, v5
	v_mul_f32_e32 v9, v7, v7
	v_fmac_f32_e32 v9, v6, v6
	v_fmac_f32_e32 v10, v4, v4
	v_add_f32_e32 v9, v9, v10
	v_add_f32_e32 v12, v8, v9
	v_pk_mul_f32 v[10:11], v[36:37], v[48:49] op_sel_hi:[0,1]
	v_pk_mul_f32 v[8:9], v[36:37], v[52:53] op_sel_hi:[0,1]
	v_pk_fma_f32 v[8:9], v[8:9], v[146:147], v[46:47]
	v_pk_fma_f32 v[10:11], v[10:11], v[144:145], v[44:45]
	v_mul_f32_e32 v14, v9, v9
	v_mul_f32_e32 v13, v11, v11
	v_fmac_f32_e32 v13, v10, v10
	v_fmac_f32_e32 v14, v8, v8
	v_add_f32_e32 v13, v13, v14
	v_add_f32_e32 v16, v12, v13
	v_pk_mul_f32 v[14:15], v[36:37], v[54:55] op_sel_hi:[0,1]
	v_pk_mul_f32 v[12:13], v[36:37], v[64:65] op_sel_hi:[0,1]
	v_pk_fma_f32 v[12:13], v[12:13], v[142:143], v[42:43]
	v_pk_fma_f32 v[14:15], v[14:15], v[140:141], v[50:51]
	v_mul_f32_e32 v18, v13, v13
	v_mul_f32_e32 v17, v15, v15
	v_fmac_f32_e32 v17, v14, v14
	v_fmac_f32_e32 v18, v12, v12
	v_add_f32_e32 v17, v17, v18
	v_add_f32_e32 v16, v16, v17
	s_nop 1
	v_add_f32_dpp v16, v16, v16 quad_perm:[1,0,3,2] row_mask:0xf bank_mask:0xf bound_ctrl:1
	s_nop 1
	v_add_f32_dpp v16, v16, v16 quad_perm:[2,3,0,1] row_mask:0xf bank_mask:0xf bound_ctrl:1
	s_nop 1
	v_add_f32_dpp v16, v16, v16 row_half_mirror row_mask:0xf bank_mask:0xf bound_ctrl:1
	s_nop 1
	v_add_f32_dpp v16, v16, v16 row_mirror row_mask:0xf bank_mask:0xf bound_ctrl:1
	s_nop 0
	v_readlane_b32 s1, v16, 16
	v_readlane_b32 s0, v16, 0
	s_nop 0
	v_mov_b32_e32 v17, s1
	v_readlane_b32 s1, v16, 48
	v_add_f32_e32 v17, s0, v17
	v_readlane_b32 s0, v16, 32
	v_mov_b32_e32 v16, s1
	s_nop 0
	v_add_f32_e32 v16, s0, v16
	v_add_f32_e32 v16, v17, v16
	v_fmamk_f32 v16, v16, 0x3a800000, v84
	s_and_saveexec_b64 s[4:5], s[6:7]
	s_cbranch_execz .LBB0_1158
	v_mul_f32_e32 v17, 0x4f800000, v16
	v_cmp_gt_f32_e32 vcc, s9, v16
	s_add_u32 s22, s92, s10
	s_addc_u32 s23, s93, s11
	v_cndmask_b32_e32 v17, v16, v17, vcc
	v_sqrt_f32_e32 v18, v17
	s_nop 0
	v_add_u32_e32 v19, -1, v18
	v_fma_f32 v20, -v19, v18, v17
	v_cmp_ge_f32_e64 s[0:1], 0, v20
	v_add_u32_e32 v20, 1, v18
	s_nop 0
	v_cndmask_b32_e64 v19, v18, v19, s[0:1]
	v_fma_f32 v18, -v20, v18, v17
	v_cmp_lt_f32_e64 s[0:1], 0, v18
	s_nop 1
	v_cndmask_b32_e64 v18, v19, v20, s[0:1]
	v_mul_f32_e32 v19, 0x37800000, v18
	v_cndmask_b32_e32 v18, v18, v19, vcc
	v_cmp_class_f32_e32 vcc, v17, v85
	s_nop 1
	v_cndmask_b32_e32 v17, v18, v17, vcc
	global_store_dword v86, v17, s[22:23] offset:3072
	s_branch .LBB0_1158
